# priority 1 during GEMM1 tile epilogue + queue dispatch, 0 in the K-loop
# speedup vs baseline: 1.0271x; 1.0271x over previous
.LBB0_346:
	s_setprio 0
	v_and_b32_e32 v76, 63, v0
	v_lshrrev_b32_e32 v77, 6, v0
	v_and_b32_e32 v93, 15, v0
	v_readfirstlane_b32 s9, v77
	v_lshrrev_b32_e32 v78, 3, v76
	v_and_b32_e32 v79, 7, v76
	v_lshrrev_b32_e32 v80, 1, v78
	s_and_b32 s4, s9, 1
	s_lshl_b32 s4, s4, 2
	v_or_b32_e32 v80, s4, v80
	v_xor_b32_e32 v79, v79, v80
	s_lshl_b32 s4, s9, 3
	v_add_u32_e32 v78, s4, v78
	v_lshlrev_b32_e32 v78, 11, v78
	v_lshl_add_u32 v56, v79, 4, v78
	v_add_u32_e32 v57, 0x10000, v56
	v_add_u32_e32 v58, 0x20000, v56
	v_add_u32_e32 v59, 0x30000, v56
	s_lshl_b32 s4, s22, 18
	s_add_u32 s0, s48, s4
	s_addc_u32 s1, s49, 0
	s_lshl_b32 s4, s64, 18
	s_add_u32 s2, s44, s4
	s_addc_u32 s3, s45, 0
	s_lshl_b32 s4, s9, 10
	s_add_u32 s4, s4, 16
	v_bfe_u32 v2, v0, 4, 2
	v_bfe_u32 v81, v0, 1, 3
	v_xor_b32_e32 v82, v2, v81
	v_or_b32_e32 v83, 4, v2
	v_xor_b32_e32 v83, v83, v81
	v_lshlrev_b32_e32 v82, 4, v82
	v_lshlrev_b32_e32 v83, 4, v83
	v_lshlrev_b32_e32 v84, 7, v93
	v_ashrrev_i32_e32 v92, 7, v0
	s_lshr_b32 s9, s9, 1
	s_lshl_b32 s9, s9, 13
	v_add3_u32 v64, v84, s9, 16
	v_add_u32_e32 v65, v64, v83
	v_add_u32_e32 v64, v64, v82
	v_bfe_u32 v85, v0, 6, 1
	s_lshl_b32 s9, s64, 7
	v_lshl_or_b32 v94, v85, 6, s9
	v_lshlrev_b32_e32 v85, 13, v85
	v_add3_u32 v66, v84, v85, 16
	v_add_u32_e32 v66, 0x4000, v66
	v_add_u32_e32 v67, v66, v83
	v_add_u32_e32 v66, v66, v82
	v_mov_b32_e32 v60, 0
	v_mov_b32_e32 v61, 0
	v_mov_b32_e32 v62, 0
	v_mov_b32_e32 v63, 0
	v_mov_b32_e32 v68, 0
	v_mov_b32_e32 v69, 0
	v_mov_b32_e32 v70, 0
	v_mov_b32_e32 v71, 0
	v_mov_b32_e32 v52, 0
	v_mov_b32_e32 v53, 0
	v_mov_b32_e32 v54, 0
	v_mov_b32_e32 v55, 0
	v_mov_b32_e32 v40, 0
	v_mov_b32_e32 v41, 0
	v_mov_b32_e32 v42, 0
	v_mov_b32_e32 v43, 0
	v_mov_b32_e32 v72, 0
	v_mov_b32_e32 v73, 0
	v_mov_b32_e32 v74, 0
	v_mov_b32_e32 v75, 0
	v_mov_b32_e32 v48, 0
	v_mov_b32_e32 v49, 0
	v_mov_b32_e32 v50, 0
	v_mov_b32_e32 v51, 0
	v_mov_b32_e32 v44, 0
	v_mov_b32_e32 v45, 0
	v_mov_b32_e32 v46, 0
	v_mov_b32_e32 v47, 0
	v_mov_b32_e32 v36, 0
	v_mov_b32_e32 v37, 0
	v_mov_b32_e32 v38, 0
	v_mov_b32_e32 v39, 0
	v_mov_b32_e32 v32, 0
	v_mov_b32_e32 v33, 0
	v_mov_b32_e32 v34, 0
	v_mov_b32_e32 v35, 0
	v_mov_b32_e32 v28, 0
	v_mov_b32_e32 v29, 0
	v_mov_b32_e32 v30, 0
	v_mov_b32_e32 v31, 0
	v_mov_b32_e32 v24, 0
	v_mov_b32_e32 v25, 0
	v_mov_b32_e32 v26, 0
	v_mov_b32_e32 v27, 0
	v_mov_b32_e32 v20, 0
	v_mov_b32_e32 v21, 0
	v_mov_b32_e32 v22, 0
	v_mov_b32_e32 v23, 0
	v_mov_b32_e32 v16, 0
	v_mov_b32_e32 v17, 0
	v_mov_b32_e32 v18, 0
	v_mov_b32_e32 v19, 0
	v_mov_b32_e32 v12, 0
	v_mov_b32_e32 v13, 0
	v_mov_b32_e32 v14, 0
	v_mov_b32_e32 v15, 0
	v_mov_b32_e32 v8, 0
	v_mov_b32_e32 v9, 0
	v_mov_b32_e32 v10, 0
	v_mov_b32_e32 v11, 0
	v_mov_b32_e32 v4, 0
	v_mov_b32_e32 v5, 0
	v_mov_b32_e32 v6, 0
	v_mov_b32_e32 v7, 0
	s_cmp_eq_u32 s64, 24
	s_cbranch_scc1 .Lg1_narrow
	s_add_u32 m0, s4, 0x0
	s_nop 0
	global_load_lds_dwordx4 v56, s[0:1]
	s_add_u32 m0, s4, 0x1000
	s_nop 0
	global_load_lds_dwordx4 v57, s[0:1]
	s_add_u32 m0, s4, 0x2000
	s_nop 0
	global_load_lds_dwordx4 v58, s[0:1]
	s_add_u32 m0, s4, 0x3000
	s_nop 0
	global_load_lds_dwordx4 v59, s[0:1]
	s_add_u32 m0, s4, 0x4000
	s_nop 0
	global_load_lds_dwordx4 v56, s[2:3]
	s_add_u32 m0, s4, 0x5000
	s_nop 0
	global_load_lds_dwordx4 v57, s[2:3]
	s_add_u32 m0, s4, 0x6000
	s_nop 0
	global_load_lds_dwordx4 v58, s[2:3]
	s_add_u32 m0, s4, 0x7000
	s_nop 0
	global_load_lds_dwordx4 v59, s[2:3]
	s_add_u32 s0, s0, 0x80
	s_addc_u32 s1, s1, 0
	s_add_u32 s2, s2, 0x80
	s_addc_u32 s3, s3, 0
	s_waitcnt vmcnt(0)
	s_barrier
	ds_read_b128 v[140:143], v66 offset:0
	ds_read_b128 v[144:147], v66 offset:2048
	ds_read_b128 v[148:151], v66 offset:4096
	ds_read_b128 v[152:155], v66 offset:6144
	ds_read_b128 v[156:159], v64 offset:0
	ds_read_b128 v[160:163], v64 offset:2048
	ds_read_b128 v[164:167], v64 offset:4096
	ds_read_b128 v[168:171], v64 offset:6144
	s_waitcnt lgkmcnt(0)
	ds_read_b128 v[172:175], v67 offset:0
	ds_read_b128 v[176:179], v67 offset:2048
	ds_read_b128 v[180:183], v67 offset:4096
	ds_read_b128 v[184:187], v67 offset:6144
	ds_read_b128 v[188:191], v65 offset:0
	ds_read_b128 v[192:195], v65 offset:2048
	ds_read_b128 v[196:199], v65 offset:4096
	ds_read_b128 v[200:203], v65 offset:6144
	v_mfma_f32_16x16x32_bf16 v[60:63], v[140:143], v[156:159], v[60:63]
	v_mfma_f32_16x16x32_bf16 v[68:71], v[140:143], v[160:163], v[68:71]
	s_add_u32 m0, s4, 0x8000
	s_nop 0
	global_load_lds_dwordx4 v56, s[0:1]
	v_mfma_f32_16x16x32_bf16 v[52:55], v[140:143], v[164:167], v[52:55]
	v_mfma_f32_16x16x32_bf16 v[40:43], v[140:143], v[168:171], v[40:43]
	s_add_u32 m0, s4, 0x9000
	s_nop 0
	global_load_lds_dwordx4 v57, s[0:1]
	v_mfma_f32_16x16x32_bf16 v[72:75], v[144:147], v[156:159], v[72:75]
	v_mfma_f32_16x16x32_bf16 v[48:51], v[144:147], v[160:163], v[48:51]
	s_add_u32 m0, s4, 0xa000
	s_nop 0
	global_load_lds_dwordx4 v58, s[0:1]
	v_mfma_f32_16x16x32_bf16 v[44:47], v[144:147], v[164:167], v[44:47]
	v_mfma_f32_16x16x32_bf16 v[36:39], v[144:147], v[168:171], v[36:39]
	s_add_u32 m0, s4, 0xb000
	s_nop 0
	global_load_lds_dwordx4 v59, s[0:1]
	v_mfma_f32_16x16x32_bf16 v[32:35], v[148:151], v[156:159], v[32:35]
	v_mfma_f32_16x16x32_bf16 v[28:31], v[148:151], v[160:163], v[28:31]
	s_add_u32 m0, s4, 0xc000
	s_nop 0
	global_load_lds_dwordx4 v56, s[2:3]
	v_mfma_f32_16x16x32_bf16 v[24:27], v[148:151], v[164:167], v[24:27]
	v_mfma_f32_16x16x32_bf16 v[20:23], v[148:151], v[168:171], v[20:23]
	s_add_u32 m0, s4, 0xd000
	s_nop 0
	global_load_lds_dwordx4 v57, s[2:3]
	v_mfma_f32_16x16x32_bf16 v[16:19], v[152:155], v[156:159], v[16:19]
	v_mfma_f32_16x16x32_bf16 v[12:15], v[152:155], v[160:163], v[12:15]
	s_add_u32 m0, s4, 0xe000
	s_nop 0
	global_load_lds_dwordx4 v58, s[2:3]
	v_mfma_f32_16x16x32_bf16 v[8:11], v[152:155], v[164:167], v[8:11]
	v_mfma_f32_16x16x32_bf16 v[4:7], v[152:155], v[168:171], v[4:7]
	s_add_u32 m0, s4, 0xf000
	s_nop 0
	global_load_lds_dwordx4 v59, s[2:3]
	s_add_u32 s0, s0, 0x80
	s_addc_u32 s1, s1, 0
	s_add_u32 s2, s2, 0x80
	s_addc_u32 s3, s3, 0
	s_waitcnt vmcnt(0) lgkmcnt(0)
	s_barrier
	ds_read_b128 v[140:143], v66 offset:32768
	ds_read_b128 v[144:147], v66 offset:34816
	ds_read_b128 v[148:151], v66 offset:36864
	ds_read_b128 v[152:155], v66 offset:38912
	ds_read_b128 v[156:159], v64 offset:32768
	ds_read_b128 v[160:163], v64 offset:34816
	ds_read_b128 v[164:167], v64 offset:36864
	ds_read_b128 v[168:171], v64 offset:38912
	v_mfma_f32_16x16x32_bf16 v[60:63], v[172:175], v[188:191], v[60:63]
	v_mfma_f32_16x16x32_bf16 v[68:71], v[172:175], v[192:195], v[68:71]
	v_mfma_f32_16x16x32_bf16 v[52:55], v[172:175], v[196:199], v[52:55]
	v_mfma_f32_16x16x32_bf16 v[40:43], v[172:175], v[200:203], v[40:43]
	v_mfma_f32_16x16x32_bf16 v[72:75], v[176:179], v[188:191], v[72:75]
	v_mfma_f32_16x16x32_bf16 v[48:51], v[176:179], v[192:195], v[48:51]
	v_mfma_f32_16x16x32_bf16 v[44:47], v[176:179], v[196:199], v[44:47]
	v_mfma_f32_16x16x32_bf16 v[36:39], v[176:179], v[200:203], v[36:39]
	v_mfma_f32_16x16x32_bf16 v[32:35], v[180:183], v[188:191], v[32:35]
	v_mfma_f32_16x16x32_bf16 v[28:31], v[180:183], v[192:195], v[28:31]
	v_mfma_f32_16x16x32_bf16 v[24:27], v[180:183], v[196:199], v[24:27]
	v_mfma_f32_16x16x32_bf16 v[20:23], v[180:183], v[200:203], v[20:23]
	v_mfma_f32_16x16x32_bf16 v[16:19], v[184:187], v[188:191], v[16:19]
	v_mfma_f32_16x16x32_bf16 v[12:15], v[184:187], v[192:195], v[12:15]
	v_mfma_f32_16x16x32_bf16 v[8:11], v[184:187], v[196:199], v[8:11]
	v_mfma_f32_16x16x32_bf16 v[4:7], v[184:187], v[200:203], v[4:7]
	s_waitcnt lgkmcnt(0)
	ds_read_b128 v[172:175], v67 offset:32768
	ds_read_b128 v[176:179], v67 offset:34816
	ds_read_b128 v[180:183], v67 offset:36864
	ds_read_b128 v[184:187], v67 offset:38912
	ds_read_b128 v[188:191], v65 offset:32768
	ds_read_b128 v[192:195], v65 offset:34816
	ds_read_b128 v[196:199], v65 offset:36864
	ds_read_b128 v[200:203], v65 offset:38912
	v_mfma_f32_16x16x32_bf16 v[60:63], v[140:143], v[156:159], v[60:63]
	v_mfma_f32_16x16x32_bf16 v[68:71], v[140:143], v[160:163], v[68:71]
	s_add_u32 m0, s4, 0x0
	s_nop 0
	global_load_lds_dwordx4 v56, s[0:1]
	v_mfma_f32_16x16x32_bf16 v[52:55], v[140:143], v[164:167], v[52:55]
	v_mfma_f32_16x16x32_bf16 v[40:43], v[140:143], v[168:171], v[40:43]
	s_add_u32 m0, s4, 0x1000
	s_nop 0
	global_load_lds_dwordx4 v57, s[0:1]
	v_mfma_f32_16x16x32_bf16 v[72:75], v[144:147], v[156:159], v[72:75]
	v_mfma_f32_16x16x32_bf16 v[48:51], v[144:147], v[160:163], v[48:51]
	s_add_u32 m0, s4, 0x2000
	s_nop 0
	global_load_lds_dwordx4 v58, s[0:1]
	v_mfma_f32_16x16x32_bf16 v[44:47], v[144:147], v[164:167], v[44:47]
	v_mfma_f32_16x16x32_bf16 v[36:39], v[144:147], v[168:171], v[36:39]
	s_add_u32 m0, s4, 0x3000
	s_nop 0
	global_load_lds_dwordx4 v59, s[0:1]
	v_mfma_f32_16x16x32_bf16 v[32:35], v[148:151], v[156:159], v[32:35]
	v_mfma_f32_16x16x32_bf16 v[28:31], v[148:151], v[160:163], v[28:31]
	s_add_u32 m0, s4, 0x4000
	s_nop 0
	global_load_lds_dwordx4 v56, s[2:3]
	v_mfma_f32_16x16x32_bf16 v[24:27], v[148:151], v[164:167], v[24:27]
	v_mfma_f32_16x16x32_bf16 v[20:23], v[148:151], v[168:171], v[20:23]
	s_add_u32 m0, s4, 0x5000
	s_nop 0
	global_load_lds_dwordx4 v57, s[2:3]
	v_mfma_f32_16x16x32_bf16 v[16:19], v[152:155], v[156:159], v[16:19]
	v_mfma_f32_16x16x32_bf16 v[12:15], v[152:155], v[160:163], v[12:15]
	s_add_u32 m0, s4, 0x6000
	s_nop 0
	global_load_lds_dwordx4 v58, s[2:3]
	v_mfma_f32_16x16x32_bf16 v[8:11], v[152:155], v[164:167], v[8:11]
	v_mfma_f32_16x16x32_bf16 v[4:7], v[152:155], v[168:171], v[4:7]
	s_add_u32 m0, s4, 0x7000
	s_nop 0
	global_load_lds_dwordx4 v59, s[2:3]
	s_add_u32 s0, s0, 0x80
	s_addc_u32 s1, s1, 0
	s_add_u32 s2, s2, 0x80
	s_addc_u32 s3, s3, 0
	s_waitcnt vmcnt(0) lgkmcnt(0)
	s_barrier
	ds_read_b128 v[140:143], v66 offset:0
	ds_read_b128 v[144:147], v66 offset:2048
	ds_read_b128 v[148:151], v66 offset:4096
	ds_read_b128 v[152:155], v66 offset:6144
	ds_read_b128 v[156:159], v64 offset:0
	ds_read_b128 v[160:163], v64 offset:2048
	ds_read_b128 v[164:167], v64 offset:4096
	ds_read_b128 v[168:171], v64 offset:6144
	v_mfma_f32_16x16x32_bf16 v[60:63], v[172:175], v[188:191], v[60:63]
	v_mfma_f32_16x16x32_bf16 v[68:71], v[172:175], v[192:195], v[68:71]
	v_mfma_f32_16x16x32_bf16 v[52:55], v[172:175], v[196:199], v[52:55]
	v_mfma_f32_16x16x32_bf16 v[40:43], v[172:175], v[200:203], v[40:43]
	v_mfma_f32_16x16x32_bf16 v[72:75], v[176:179], v[188:191], v[72:75]
	v_mfma_f32_16x16x32_bf16 v[48:51], v[176:179], v[192:195], v[48:51]
	v_mfma_f32_16x16x32_bf16 v[44:47], v[176:179], v[196:199], v[44:47]
	v_mfma_f32_16x16x32_bf16 v[36:39], v[176:179], v[200:203], v[36:39]
	v_mfma_f32_16x16x32_bf16 v[32:35], v[180:183], v[188:191], v[32:35]
	v_mfma_f32_16x16x32_bf16 v[28:31], v[180:183], v[192:195], v[28:31]
	v_mfma_f32_16x16x32_bf16 v[24:27], v[180:183], v[196:199], v[24:27]
	v_mfma_f32_16x16x32_bf16 v[20:23], v[180:183], v[200:203], v[20:23]
	v_mfma_f32_16x16x32_bf16 v[16:19], v[184:187], v[188:191], v[16:19]
	v_mfma_f32_16x16x32_bf16 v[12:15], v[184:187], v[192:195], v[12:15]
	v_mfma_f32_16x16x32_bf16 v[8:11], v[184:187], v[196:199], v[8:11]
	v_mfma_f32_16x16x32_bf16 v[4:7], v[184:187], v[200:203], v[4:7]
	s_waitcnt lgkmcnt(0)
	ds_read_b128 v[172:175], v67 offset:0
	ds_read_b128 v[176:179], v67 offset:2048
	ds_read_b128 v[180:183], v67 offset:4096
	ds_read_b128 v[184:187], v67 offset:6144
	ds_read_b128 v[188:191], v65 offset:0
	ds_read_b128 v[192:195], v65 offset:2048
	ds_read_b128 v[196:199], v65 offset:4096
	ds_read_b128 v[200:203], v65 offset:6144
	v_mfma_f32_16x16x32_bf16 v[60:63], v[140:143], v[156:159], v[60:63]
	v_mfma_f32_16x16x32_bf16 v[68:71], v[140:143], v[160:163], v[68:71]
	s_add_u32 m0, s4, 0x8000
	s_nop 0
	global_load_lds_dwordx4 v56, s[0:1]
	v_mfma_f32_16x16x32_bf16 v[52:55], v[140:143], v[164:167], v[52:55]
	v_mfma_f32_16x16x32_bf16 v[40:43], v[140:143], v[168:171], v[40:43]
	s_add_u32 m0, s4, 0x9000
	s_nop 0
	global_load_lds_dwordx4 v57, s[0:1]
	v_mfma_f32_16x16x32_bf16 v[72:75], v[144:147], v[156:159], v[72:75]
	v_mfma_f32_16x16x32_bf16 v[48:51], v[144:147], v[160:163], v[48:51]
	s_add_u32 m0, s4, 0xa000
	s_nop 0
	global_load_lds_dwordx4 v58, s[0:1]
	v_mfma_f32_16x16x32_bf16 v[44:47], v[144:147], v[164:167], v[44:47]
	v_mfma_f32_16x16x32_bf16 v[36:39], v[144:147], v[168:171], v[36:39]
	s_add_u32 m0, s4, 0xb000
	s_nop 0
	global_load_lds_dwordx4 v59, s[0:1]
	v_mfma_f32_16x16x32_bf16 v[32:35], v[148:151], v[156:159], v[32:35]
	v_mfma_f32_16x16x32_bf16 v[28:31], v[148:151], v[160:163], v[28:31]
	s_add_u32 m0, s4, 0xc000
	s_nop 0
	global_load_lds_dwordx4 v56, s[2:3]
	v_mfma_f32_16x16x32_bf16 v[24:27], v[148:151], v[164:167], v[24:27]
	v_mfma_f32_16x16x32_bf16 v[20:23], v[148:151], v[168:171], v[20:23]
	s_add_u32 m0, s4, 0xd000
	s_nop 0
	global_load_lds_dwordx4 v57, s[2:3]
	v_mfma_f32_16x16x32_bf16 v[16:19], v[152:155], v[156:159], v[16:19]
	v_mfma_f32_16x16x32_bf16 v[12:15], v[152:155], v[160:163], v[12:15]
	s_add_u32 m0, s4, 0xe000
	s_nop 0
	global_load_lds_dwordx4 v58, s[2:3]
	v_mfma_f32_16x16x32_bf16 v[8:11], v[152:155], v[164:167], v[8:11]
	v_mfma_f32_16x16x32_bf16 v[4:7], v[152:155], v[168:171], v[4:7]
	s_add_u32 m0, s4, 0xf000
	s_nop 0
	global_load_lds_dwordx4 v59, s[2:3]
	s_add_u32 s0, s0, 0x80
	s_addc_u32 s1, s1, 0
	s_add_u32 s2, s2, 0x80
	s_addc_u32 s3, s3, 0
	s_waitcnt vmcnt(0) lgkmcnt(0)
	s_barrier
	ds_read_b128 v[140:143], v66 offset:32768
	ds_read_b128 v[144:147], v66 offset:34816
	ds_read_b128 v[148:151], v66 offset:36864
	ds_read_b128 v[152:155], v66 offset:38912
	ds_read_b128 v[156:159], v64 offset:32768
	ds_read_b128 v[160:163], v64 offset:34816
	ds_read_b128 v[164:167], v64 offset:36864
	ds_read_b128 v[168:171], v64 offset:38912
	v_mfma_f32_16x16x32_bf16 v[60:63], v[172:175], v[188:191], v[60:63]
	v_mfma_f32_16x16x32_bf16 v[68:71], v[172:175], v[192:195], v[68:71]
	v_mfma_f32_16x16x32_bf16 v[52:55], v[172:175], v[196:199], v[52:55]
	v_mfma_f32_16x16x32_bf16 v[40:43], v[172:175], v[200:203], v[40:43]
	v_mfma_f32_16x16x32_bf16 v[72:75], v[176:179], v[188:191], v[72:75]
	v_mfma_f32_16x16x32_bf16 v[48:51], v[176:179], v[192:195], v[48:51]
	v_mfma_f32_16x16x32_bf16 v[44:47], v[176:179], v[196:199], v[44:47]
	v_mfma_f32_16x16x32_bf16 v[36:39], v[176:179], v[200:203], v[36:39]
	v_mfma_f32_16x16x32_bf16 v[32:35], v[180:183], v[188:191], v[32:35]
	v_mfma_f32_16x16x32_bf16 v[28:31], v[180:183], v[192:195], v[28:31]
	v_mfma_f32_16x16x32_bf16 v[24:27], v[180:183], v[196:199], v[24:27]
	v_mfma_f32_16x16x32_bf16 v[20:23], v[180:183], v[200:203], v[20:23]
	v_mfma_f32_16x16x32_bf16 v[16:19], v[184:187], v[188:191], v[16:19]
	v_mfma_f32_16x16x32_bf16 v[12:15], v[184:187], v[192:195], v[12:15]
	v_mfma_f32_16x16x32_bf16 v[8:11], v[184:187], v[196:199], v[8:11]
	v_mfma_f32_16x16x32_bf16 v[4:7], v[184:187], v[200:203], v[4:7]
	s_waitcnt lgkmcnt(0)
	ds_read_b128 v[172:175], v67 offset:32768
	ds_read_b128 v[176:179], v67 offset:34816
	ds_read_b128 v[180:183], v67 offset:36864
	ds_read_b128 v[184:187], v67 offset:38912
	ds_read_b128 v[188:191], v65 offset:32768
	ds_read_b128 v[192:195], v65 offset:34816
	ds_read_b128 v[196:199], v65 offset:36864
	ds_read_b128 v[200:203], v65 offset:38912
	v_mfma_f32_16x16x32_bf16 v[60:63], v[140:143], v[156:159], v[60:63]
	v_mfma_f32_16x16x32_bf16 v[68:71], v[140:143], v[160:163], v[68:71]
	s_add_u32 m0, s4, 0x0
	s_nop 0
	global_load_lds_dwordx4 v56, s[0:1]
	v_mfma_f32_16x16x32_bf16 v[52:55], v[140:143], v[164:167], v[52:55]
	v_mfma_f32_16x16x32_bf16 v[40:43], v[140:143], v[168:171], v[40:43]
	s_add_u32 m0, s4, 0x1000
	s_nop 0
	global_load_lds_dwordx4 v57, s[0:1]
	v_mfma_f32_16x16x32_bf16 v[72:75], v[144:147], v[156:159], v[72:75]
	v_mfma_f32_16x16x32_bf16 v[48:51], v[144:147], v[160:163], v[48:51]
	s_add_u32 m0, s4, 0x2000
	s_nop 0
	global_load_lds_dwordx4 v58, s[0:1]
	v_mfma_f32_16x16x32_bf16 v[44:47], v[144:147], v[164:167], v[44:47]
	v_mfma_f32_16x16x32_bf16 v[36:39], v[144:147], v[168:171], v[36:39]
	s_add_u32 m0, s4, 0x3000
	s_nop 0
	global_load_lds_dwordx4 v59, s[0:1]
	v_mfma_f32_16x16x32_bf16 v[32:35], v[148:151], v[156:159], v[32:35]
	v_mfma_f32_16x16x32_bf16 v[28:31], v[148:151], v[160:163], v[28:31]
	s_add_u32 m0, s4, 0x4000
	s_nop 0
	global_load_lds_dwordx4 v56, s[2:3]
	v_mfma_f32_16x16x32_bf16 v[24:27], v[148:151], v[164:167], v[24:27]
	v_mfma_f32_16x16x32_bf16 v[20:23], v[148:151], v[168:171], v[20:23]
	s_add_u32 m0, s4, 0x5000
	s_nop 0
	global_load_lds_dwordx4 v57, s[2:3]
	v_mfma_f32_16x16x32_bf16 v[16:19], v[152:155], v[156:159], v[16:19]
	v_mfma_f32_16x16x32_bf16 v[12:15], v[152:155], v[160:163], v[12:15]
	s_add_u32 m0, s4, 0x6000
	s_nop 0
	global_load_lds_dwordx4 v58, s[2:3]
	v_mfma_f32_16x16x32_bf16 v[8:11], v[152:155], v[164:167], v[8:11]
	v_mfma_f32_16x16x32_bf16 v[4:7], v[152:155], v[168:171], v[4:7]
	s_add_u32 m0, s4, 0x7000
	s_nop 0
	global_load_lds_dwordx4 v59, s[2:3]
	s_add_u32 s0, s0, 0x80
	s_addc_u32 s1, s1, 0
	s_add_u32 s2, s2, 0x80
	s_addc_u32 s3, s3, 0
	s_waitcnt vmcnt(0) lgkmcnt(0)
	s_barrier
	ds_read_b128 v[140:143], v66 offset:0
	ds_read_b128 v[144:147], v66 offset:2048
	ds_read_b128 v[148:151], v66 offset:4096
	ds_read_b128 v[152:155], v66 offset:6144
	ds_read_b128 v[156:159], v64 offset:0
	ds_read_b128 v[160:163], v64 offset:2048
	ds_read_b128 v[164:167], v64 offset:4096
	ds_read_b128 v[168:171], v64 offset:6144
	v_mfma_f32_16x16x32_bf16 v[60:63], v[172:175], v[188:191], v[60:63]
	v_mfma_f32_16x16x32_bf16 v[68:71], v[172:175], v[192:195], v[68:71]
	v_mfma_f32_16x16x32_bf16 v[52:55], v[172:175], v[196:199], v[52:55]
	v_mfma_f32_16x16x32_bf16 v[40:43], v[172:175], v[200:203], v[40:43]
	v_mfma_f32_16x16x32_bf16 v[72:75], v[176:179], v[188:191], v[72:75]
	v_mfma_f32_16x16x32_bf16 v[48:51], v[176:179], v[192:195], v[48:51]
	v_mfma_f32_16x16x32_bf16 v[44:47], v[176:179], v[196:199], v[44:47]
	v_mfma_f32_16x16x32_bf16 v[36:39], v[176:179], v[200:203], v[36:39]
	v_mfma_f32_16x16x32_bf16 v[32:35], v[180:183], v[188:191], v[32:35]
	v_mfma_f32_16x16x32_bf16 v[28:31], v[180:183], v[192:195], v[28:31]
	v_mfma_f32_16x16x32_bf16 v[24:27], v[180:183], v[196:199], v[24:27]
	v_mfma_f32_16x16x32_bf16 v[20:23], v[180:183], v[200:203], v[20:23]
	v_mfma_f32_16x16x32_bf16 v[16:19], v[184:187], v[188:191], v[16:19]
	v_mfma_f32_16x16x32_bf16 v[12:15], v[184:187], v[192:195], v[12:15]
	v_mfma_f32_16x16x32_bf16 v[8:11], v[184:187], v[196:199], v[8:11]
	v_mfma_f32_16x16x32_bf16 v[4:7], v[184:187], v[200:203], v[4:7]
	s_waitcnt lgkmcnt(0)
	ds_read_b128 v[172:175], v67 offset:0
	ds_read_b128 v[176:179], v67 offset:2048
	ds_read_b128 v[180:183], v67 offset:4096
	ds_read_b128 v[184:187], v67 offset:6144
	ds_read_b128 v[188:191], v65 offset:0
	ds_read_b128 v[192:195], v65 offset:2048
	ds_read_b128 v[196:199], v65 offset:4096
	ds_read_b128 v[200:203], v65 offset:6144
	v_mfma_f32_16x16x32_bf16 v[60:63], v[140:143], v[156:159], v[60:63]
	v_mfma_f32_16x16x32_bf16 v[68:71], v[140:143], v[160:163], v[68:71]
	s_add_u32 m0, s4, 0x8000
	s_nop 0
	global_load_lds_dwordx4 v56, s[0:1]
	v_mfma_f32_16x16x32_bf16 v[52:55], v[140:143], v[164:167], v[52:55]
	v_mfma_f32_16x16x32_bf16 v[40:43], v[140:143], v[168:171], v[40:43]
	s_add_u32 m0, s4, 0x9000
	s_nop 0
	global_load_lds_dwordx4 v57, s[0:1]
	v_mfma_f32_16x16x32_bf16 v[72:75], v[144:147], v[156:159], v[72:75]
	v_mfma_f32_16x16x32_bf16 v[48:51], v[144:147], v[160:163], v[48:51]
	s_add_u32 m0, s4, 0xa000
	s_nop 0
	global_load_lds_dwordx4 v58, s[0:1]
	v_mfma_f32_16x16x32_bf16 v[44:47], v[144:147], v[164:167], v[44:47]
	v_mfma_f32_16x16x32_bf16 v[36:39], v[144:147], v[168:171], v[36:39]
	s_add_u32 m0, s4, 0xb000
	s_nop 0
	global_load_lds_dwordx4 v59, s[0:1]
	v_mfma_f32_16x16x32_bf16 v[32:35], v[148:151], v[156:159], v[32:35]
	v_mfma_f32_16x16x32_bf16 v[28:31], v[148:151], v[160:163], v[28:31]
	s_add_u32 m0, s4, 0xc000
	s_nop 0
	global_load_lds_dwordx4 v56, s[2:3]
	v_mfma_f32_16x16x32_bf16 v[24:27], v[148:151], v[164:167], v[24:27]
	v_mfma_f32_16x16x32_bf16 v[20:23], v[148:151], v[168:171], v[20:23]
	s_add_u32 m0, s4, 0xd000
	s_nop 0
	global_load_lds_dwordx4 v57, s[2:3]
	v_mfma_f32_16x16x32_bf16 v[16:19], v[152:155], v[156:159], v[16:19]
	v_mfma_f32_16x16x32_bf16 v[12:15], v[152:155], v[160:163], v[12:15]
	s_add_u32 m0, s4, 0xe000
	s_nop 0
	global_load_lds_dwordx4 v58, s[2:3]
	v_mfma_f32_16x16x32_bf16 v[8:11], v[152:155], v[164:167], v[8:11]
	v_mfma_f32_16x16x32_bf16 v[4:7], v[152:155], v[168:171], v[4:7]
	s_add_u32 m0, s4, 0xf000
	s_nop 0
	global_load_lds_dwordx4 v59, s[2:3]
	s_add_u32 s0, s0, 0x80
	s_addc_u32 s1, s1, 0
	s_add_u32 s2, s2, 0x80
	s_addc_u32 s3, s3, 0
	s_waitcnt vmcnt(0) lgkmcnt(0)
	s_barrier
	ds_read_b128 v[140:143], v66 offset:32768
	ds_read_b128 v[144:147], v66 offset:34816
	ds_read_b128 v[148:151], v66 offset:36864
	ds_read_b128 v[152:155], v66 offset:38912
	ds_read_b128 v[156:159], v64 offset:32768
	ds_read_b128 v[160:163], v64 offset:34816
	ds_read_b128 v[164:167], v64 offset:36864
	ds_read_b128 v[168:171], v64 offset:38912
	v_mfma_f32_16x16x32_bf16 v[60:63], v[172:175], v[188:191], v[60:63]
	v_mfma_f32_16x16x32_bf16 v[68:71], v[172:175], v[192:195], v[68:71]
	v_mfma_f32_16x16x32_bf16 v[52:55], v[172:175], v[196:199], v[52:55]
	v_mfma_f32_16x16x32_bf16 v[40:43], v[172:175], v[200:203], v[40:43]
	v_mfma_f32_16x16x32_bf16 v[72:75], v[176:179], v[188:191], v[72:75]
	v_mfma_f32_16x16x32_bf16 v[48:51], v[176:179], v[192:195], v[48:51]
	v_mfma_f32_16x16x32_bf16 v[44:47], v[176:179], v[196:199], v[44:47]
	v_mfma_f32_16x16x32_bf16 v[36:39], v[176:179], v[200:203], v[36:39]
	v_mfma_f32_16x16x32_bf16 v[32:35], v[180:183], v[188:191], v[32:35]
	v_mfma_f32_16x16x32_bf16 v[28:31], v[180:183], v[192:195], v[28:31]
	v_mfma_f32_16x16x32_bf16 v[24:27], v[180:183], v[196:199], v[24:27]
	v_mfma_f32_16x16x32_bf16 v[20:23], v[180:183], v[200:203], v[20:23]
	v_mfma_f32_16x16x32_bf16 v[16:19], v[184:187], v[188:191], v[16:19]
	v_mfma_f32_16x16x32_bf16 v[12:15], v[184:187], v[192:195], v[12:15]
	v_mfma_f32_16x16x32_bf16 v[8:11], v[184:187], v[196:199], v[8:11]
	v_mfma_f32_16x16x32_bf16 v[4:7], v[184:187], v[200:203], v[4:7]
	s_waitcnt lgkmcnt(0)
	ds_read_b128 v[172:175], v67 offset:32768
	ds_read_b128 v[176:179], v67 offset:34816
	ds_read_b128 v[180:183], v67 offset:36864
	ds_read_b128 v[184:187], v67 offset:38912
	ds_read_b128 v[188:191], v65 offset:32768
	ds_read_b128 v[192:195], v65 offset:34816
	ds_read_b128 v[196:199], v65 offset:36864
	ds_read_b128 v[200:203], v65 offset:38912
	v_mfma_f32_16x16x32_bf16 v[60:63], v[140:143], v[156:159], v[60:63]
	v_mfma_f32_16x16x32_bf16 v[68:71], v[140:143], v[160:163], v[68:71]
	s_add_u32 m0, s4, 0x0
	s_nop 0
	global_load_lds_dwordx4 v56, s[0:1]
	v_mfma_f32_16x16x32_bf16 v[52:55], v[140:143], v[164:167], v[52:55]
	v_mfma_f32_16x16x32_bf16 v[40:43], v[140:143], v[168:171], v[40:43]
	s_add_u32 m0, s4, 0x1000
	s_nop 0
	global_load_lds_dwordx4 v57, s[0:1]
	v_mfma_f32_16x16x32_bf16 v[72:75], v[144:147], v[156:159], v[72:75]
	v_mfma_f32_16x16x32_bf16 v[48:51], v[144:147], v[160:163], v[48:51]
	s_add_u32 m0, s4, 0x2000
	s_nop 0
	global_load_lds_dwordx4 v58, s[0:1]
	v_mfma_f32_16x16x32_bf16 v[44:47], v[144:147], v[164:167], v[44:47]
	v_mfma_f32_16x16x32_bf16 v[36:39], v[144:147], v[168:171], v[36:39]
	s_add_u32 m0, s4, 0x3000
	s_nop 0
	global_load_lds_dwordx4 v59, s[0:1]
	v_mfma_f32_16x16x32_bf16 v[32:35], v[148:151], v[156:159], v[32:35]
	v_mfma_f32_16x16x32_bf16 v[28:31], v[148:151], v[160:163], v[28:31]
	s_add_u32 m0, s4, 0x4000
	s_nop 0
	global_load_lds_dwordx4 v56, s[2:3]
	v_mfma_f32_16x16x32_bf16 v[24:27], v[148:151], v[164:167], v[24:27]
	v_mfma_f32_16x16x32_bf16 v[20:23], v[148:151], v[168:171], v[20:23]
	s_add_u32 m0, s4, 0x5000
	s_nop 0
	global_load_lds_dwordx4 v57, s[2:3]
	v_mfma_f32_16x16x32_bf16 v[16:19], v[152:155], v[156:159], v[16:19]
	v_mfma_f32_16x16x32_bf16 v[12:15], v[152:155], v[160:163], v[12:15]
	s_add_u32 m0, s4, 0x6000
	s_nop 0
	global_load_lds_dwordx4 v58, s[2:3]
	v_mfma_f32_16x16x32_bf16 v[8:11], v[152:155], v[164:167], v[8:11]
	v_mfma_f32_16x16x32_bf16 v[4:7], v[152:155], v[168:171], v[4:7]
	s_add_u32 m0, s4, 0x7000
	s_nop 0
	global_load_lds_dwordx4 v59, s[2:3]
	s_add_u32 s0, s0, 0x80
	s_addc_u32 s1, s1, 0
	s_add_u32 s2, s2, 0x80
	s_addc_u32 s3, s3, 0
	s_waitcnt vmcnt(0) lgkmcnt(0)
	s_barrier
	ds_read_b128 v[140:143], v66 offset:0
	ds_read_b128 v[144:147], v66 offset:2048
	ds_read_b128 v[148:151], v66 offset:4096
	ds_read_b128 v[152:155], v66 offset:6144
	ds_read_b128 v[156:159], v64 offset:0
	ds_read_b128 v[160:163], v64 offset:2048
	ds_read_b128 v[164:167], v64 offset:4096
	ds_read_b128 v[168:171], v64 offset:6144
	v_mfma_f32_16x16x32_bf16 v[60:63], v[172:175], v[188:191], v[60:63]
	v_mfma_f32_16x16x32_bf16 v[68:71], v[172:175], v[192:195], v[68:71]
	v_mfma_f32_16x16x32_bf16 v[52:55], v[172:175], v[196:199], v[52:55]
	v_mfma_f32_16x16x32_bf16 v[40:43], v[172:175], v[200:203], v[40:43]
	v_mfma_f32_16x16x32_bf16 v[72:75], v[176:179], v[188:191], v[72:75]
	v_mfma_f32_16x16x32_bf16 v[48:51], v[176:179], v[192:195], v[48:51]
	v_mfma_f32_16x16x32_bf16 v[44:47], v[176:179], v[196:199], v[44:47]
	v_mfma_f32_16x16x32_bf16 v[36:39], v[176:179], v[200:203], v[36:39]
	v_mfma_f32_16x16x32_bf16 v[32:35], v[180:183], v[188:191], v[32:35]
	v_mfma_f32_16x16x32_bf16 v[28:31], v[180:183], v[192:195], v[28:31]
	v_mfma_f32_16x16x32_bf16 v[24:27], v[180:183], v[196:199], v[24:27]
	v_mfma_f32_16x16x32_bf16 v[20:23], v[180:183], v[200:203], v[20:23]
	v_mfma_f32_16x16x32_bf16 v[16:19], v[184:187], v[188:191], v[16:19]
	v_mfma_f32_16x16x32_bf16 v[12:15], v[184:187], v[192:195], v[12:15]
	v_mfma_f32_16x16x32_bf16 v[8:11], v[184:187], v[196:199], v[8:11]
	v_mfma_f32_16x16x32_bf16 v[4:7], v[184:187], v[200:203], v[4:7]
	s_waitcnt lgkmcnt(0)
	ds_read_b128 v[172:175], v67 offset:0
	ds_read_b128 v[176:179], v67 offset:2048
	ds_read_b128 v[180:183], v67 offset:4096
	ds_read_b128 v[184:187], v67 offset:6144
	ds_read_b128 v[188:191], v65 offset:0
	ds_read_b128 v[192:195], v65 offset:2048
	ds_read_b128 v[196:199], v65 offset:4096
	ds_read_b128 v[200:203], v65 offset:6144
	v_mfma_f32_16x16x32_bf16 v[60:63], v[140:143], v[156:159], v[60:63]
	v_mfma_f32_16x16x32_bf16 v[68:71], v[140:143], v[160:163], v[68:71]
	s_add_u32 m0, s4, 0x8000
	s_nop 0
	global_load_lds_dwordx4 v56, s[0:1]
	v_mfma_f32_16x16x32_bf16 v[52:55], v[140:143], v[164:167], v[52:55]
	v_mfma_f32_16x16x32_bf16 v[40:43], v[140:143], v[168:171], v[40:43]
	s_add_u32 m0, s4, 0x9000
	s_nop 0
	global_load_lds_dwordx4 v57, s[0:1]
	v_mfma_f32_16x16x32_bf16 v[72:75], v[144:147], v[156:159], v[72:75]
	v_mfma_f32_16x16x32_bf16 v[48:51], v[144:147], v[160:163], v[48:51]
	s_add_u32 m0, s4, 0xa000
	s_nop 0
	global_load_lds_dwordx4 v58, s[0:1]
	v_mfma_f32_16x16x32_bf16 v[44:47], v[144:147], v[164:167], v[44:47]
	v_mfma_f32_16x16x32_bf16 v[36:39], v[144:147], v[168:171], v[36:39]
	s_add_u32 m0, s4, 0xb000
	s_nop 0
	global_load_lds_dwordx4 v59, s[0:1]
	v_mfma_f32_16x16x32_bf16 v[32:35], v[148:151], v[156:159], v[32:35]
	v_mfma_f32_16x16x32_bf16 v[28:31], v[148:151], v[160:163], v[28:31]
	s_add_u32 m0, s4, 0xc000
	s_nop 0
	global_load_lds_dwordx4 v56, s[2:3]
	v_mfma_f32_16x16x32_bf16 v[24:27], v[148:151], v[164:167], v[24:27]
	v_mfma_f32_16x16x32_bf16 v[20:23], v[148:151], v[168:171], v[20:23]
	s_add_u32 m0, s4, 0xd000
	s_nop 0
	global_load_lds_dwordx4 v57, s[2:3]
	v_mfma_f32_16x16x32_bf16 v[16:19], v[152:155], v[156:159], v[16:19]
	v_mfma_f32_16x16x32_bf16 v[12:15], v[152:155], v[160:163], v[12:15]
	s_add_u32 m0, s4, 0xe000
	s_nop 0
	global_load_lds_dwordx4 v58, s[2:3]
	v_mfma_f32_16x16x32_bf16 v[8:11], v[152:155], v[164:167], v[8:11]
	v_mfma_f32_16x16x32_bf16 v[4:7], v[152:155], v[168:171], v[4:7]
	s_add_u32 m0, s4, 0xf000
	s_nop 0
	global_load_lds_dwordx4 v59, s[2:3]
	s_add_u32 s0, s0, 0x80
	s_addc_u32 s1, s1, 0
	s_add_u32 s2, s2, 0x80
	s_addc_u32 s3, s3, 0
	s_waitcnt vmcnt(0) lgkmcnt(0)
	s_barrier
	ds_read_b128 v[140:143], v66 offset:32768
	ds_read_b128 v[144:147], v66 offset:34816
	ds_read_b128 v[148:151], v66 offset:36864
	ds_read_b128 v[152:155], v66 offset:38912
	ds_read_b128 v[156:159], v64 offset:32768
	ds_read_b128 v[160:163], v64 offset:34816
	ds_read_b128 v[164:167], v64 offset:36864
	ds_read_b128 v[168:171], v64 offset:38912
	v_mfma_f32_16x16x32_bf16 v[60:63], v[172:175], v[188:191], v[60:63]
	v_mfma_f32_16x16x32_bf16 v[68:71], v[172:175], v[192:195], v[68:71]
	v_mfma_f32_16x16x32_bf16 v[52:55], v[172:175], v[196:199], v[52:55]
	v_mfma_f32_16x16x32_bf16 v[40:43], v[172:175], v[200:203], v[40:43]
	v_mfma_f32_16x16x32_bf16 v[72:75], v[176:179], v[188:191], v[72:75]
	v_mfma_f32_16x16x32_bf16 v[48:51], v[176:179], v[192:195], v[48:51]
	v_mfma_f32_16x16x32_bf16 v[44:47], v[176:179], v[196:199], v[44:47]
	v_mfma_f32_16x16x32_bf16 v[36:39], v[176:179], v[200:203], v[36:39]
	v_mfma_f32_16x16x32_bf16 v[32:35], v[180:183], v[188:191], v[32:35]
	v_mfma_f32_16x16x32_bf16 v[28:31], v[180:183], v[192:195], v[28:31]
	v_mfma_f32_16x16x32_bf16 v[24:27], v[180:183], v[196:199], v[24:27]
	v_mfma_f32_16x16x32_bf16 v[20:23], v[180:183], v[200:203], v[20:23]
	v_mfma_f32_16x16x32_bf16 v[16:19], v[184:187], v[188:191], v[16:19]
	v_mfma_f32_16x16x32_bf16 v[12:15], v[184:187], v[192:195], v[12:15]
	v_mfma_f32_16x16x32_bf16 v[8:11], v[184:187], v[196:199], v[8:11]
	v_mfma_f32_16x16x32_bf16 v[4:7], v[184:187], v[200:203], v[4:7]
	s_waitcnt lgkmcnt(0)
	ds_read_b128 v[172:175], v67 offset:32768
	ds_read_b128 v[176:179], v67 offset:34816
	ds_read_b128 v[180:183], v67 offset:36864
	ds_read_b128 v[184:187], v67 offset:38912
	ds_read_b128 v[188:191], v65 offset:32768
	ds_read_b128 v[192:195], v65 offset:34816
	ds_read_b128 v[196:199], v65 offset:36864
	ds_read_b128 v[200:203], v65 offset:38912
	v_mfma_f32_16x16x32_bf16 v[60:63], v[140:143], v[156:159], v[60:63]
	v_mfma_f32_16x16x32_bf16 v[68:71], v[140:143], v[160:163], v[68:71]
	s_add_u32 m0, s4, 0x0
	s_nop 0
	global_load_lds_dwordx4 v56, s[0:1]
	v_mfma_f32_16x16x32_bf16 v[52:55], v[140:143], v[164:167], v[52:55]
	v_mfma_f32_16x16x32_bf16 v[40:43], v[140:143], v[168:171], v[40:43]
	s_add_u32 m0, s4, 0x1000
	s_nop 0
	global_load_lds_dwordx4 v57, s[0:1]
	v_mfma_f32_16x16x32_bf16 v[72:75], v[144:147], v[156:159], v[72:75]
	v_mfma_f32_16x16x32_bf16 v[48:51], v[144:147], v[160:163], v[48:51]
	s_add_u32 m0, s4, 0x2000
	s_nop 0
	global_load_lds_dwordx4 v58, s[0:1]
	v_mfma_f32_16x16x32_bf16 v[44:47], v[144:147], v[164:167], v[44:47]
	v_mfma_f32_16x16x32_bf16 v[36:39], v[144:147], v[168:171], v[36:39]
	s_add_u32 m0, s4, 0x3000
	s_nop 0
	global_load_lds_dwordx4 v59, s[0:1]
	v_mfma_f32_16x16x32_bf16 v[32:35], v[148:151], v[156:159], v[32:35]
	v_mfma_f32_16x16x32_bf16 v[28:31], v[148:151], v[160:163], v[28:31]
	s_add_u32 m0, s4, 0x4000
	s_nop 0
	global_load_lds_dwordx4 v56, s[2:3]
	v_mfma_f32_16x16x32_bf16 v[24:27], v[148:151], v[164:167], v[24:27]
	v_mfma_f32_16x16x32_bf16 v[20:23], v[148:151], v[168:171], v[20:23]
	s_add_u32 m0, s4, 0x5000
	s_nop 0
	global_load_lds_dwordx4 v57, s[2:3]
	v_mfma_f32_16x16x32_bf16 v[16:19], v[152:155], v[156:159], v[16:19]
	v_mfma_f32_16x16x32_bf16 v[12:15], v[152:155], v[160:163], v[12:15]
	s_add_u32 m0, s4, 0x6000
	s_nop 0
	global_load_lds_dwordx4 v58, s[2:3]
	v_mfma_f32_16x16x32_bf16 v[8:11], v[152:155], v[164:167], v[8:11]
	v_mfma_f32_16x16x32_bf16 v[4:7], v[152:155], v[168:171], v[4:7]
	s_add_u32 m0, s4, 0x7000
	s_nop 0
	global_load_lds_dwordx4 v59, s[2:3]
	s_add_u32 s0, s0, 0x80
	s_addc_u32 s1, s1, 0
	s_add_u32 s2, s2, 0x80
	s_addc_u32 s3, s3, 0
	s_waitcnt vmcnt(0) lgkmcnt(0)
	s_barrier
	ds_read_b128 v[140:143], v66 offset:0
	ds_read_b128 v[144:147], v66 offset:2048
	ds_read_b128 v[148:151], v66 offset:4096
	ds_read_b128 v[152:155], v66 offset:6144
	ds_read_b128 v[156:159], v64 offset:0
	ds_read_b128 v[160:163], v64 offset:2048
	ds_read_b128 v[164:167], v64 offset:4096
	ds_read_b128 v[168:171], v64 offset:6144
	v_mfma_f32_16x16x32_bf16 v[60:63], v[172:175], v[188:191], v[60:63]
	v_mfma_f32_16x16x32_bf16 v[68:71], v[172:175], v[192:195], v[68:71]
	v_mfma_f32_16x16x32_bf16 v[52:55], v[172:175], v[196:199], v[52:55]
	v_mfma_f32_16x16x32_bf16 v[40:43], v[172:175], v[200:203], v[40:43]
	v_mfma_f32_16x16x32_bf16 v[72:75], v[176:179], v[188:191], v[72:75]
	v_mfma_f32_16x16x32_bf16 v[48:51], v[176:179], v[192:195], v[48:51]
	v_mfma_f32_16x16x32_bf16 v[44:47], v[176:179], v[196:199], v[44:47]
	v_mfma_f32_16x16x32_bf16 v[36:39], v[176:179], v[200:203], v[36:39]
	v_mfma_f32_16x16x32_bf16 v[32:35], v[180:183], v[188:191], v[32:35]
	v_mfma_f32_16x16x32_bf16 v[28:31], v[180:183], v[192:195], v[28:31]
	v_mfma_f32_16x16x32_bf16 v[24:27], v[180:183], v[196:199], v[24:27]
	v_mfma_f32_16x16x32_bf16 v[20:23], v[180:183], v[200:203], v[20:23]
	v_mfma_f32_16x16x32_bf16 v[16:19], v[184:187], v[188:191], v[16:19]
	v_mfma_f32_16x16x32_bf16 v[12:15], v[184:187], v[192:195], v[12:15]
	v_mfma_f32_16x16x32_bf16 v[8:11], v[184:187], v[196:199], v[8:11]
	v_mfma_f32_16x16x32_bf16 v[4:7], v[184:187], v[200:203], v[4:7]
	s_waitcnt lgkmcnt(0)
	ds_read_b128 v[172:175], v67 offset:0
	ds_read_b128 v[176:179], v67 offset:2048
	ds_read_b128 v[180:183], v67 offset:4096
	ds_read_b128 v[184:187], v67 offset:6144
	ds_read_b128 v[188:191], v65 offset:0
	ds_read_b128 v[192:195], v65 offset:2048
	ds_read_b128 v[196:199], v65 offset:4096
	ds_read_b128 v[200:203], v65 offset:6144
	v_mfma_f32_16x16x32_bf16 v[60:63], v[140:143], v[156:159], v[60:63]
	v_mfma_f32_16x16x32_bf16 v[68:71], v[140:143], v[160:163], v[68:71]
	s_add_u32 m0, s4, 0x8000
	s_nop 0
	global_load_lds_dwordx4 v56, s[0:1]
	v_mfma_f32_16x16x32_bf16 v[52:55], v[140:143], v[164:167], v[52:55]
	v_mfma_f32_16x16x32_bf16 v[40:43], v[140:143], v[168:171], v[40:43]
	s_add_u32 m0, s4, 0x9000
	s_nop 0
	global_load_lds_dwordx4 v57, s[0:1]
	v_mfma_f32_16x16x32_bf16 v[72:75], v[144:147], v[156:159], v[72:75]
	v_mfma_f32_16x16x32_bf16 v[48:51], v[144:147], v[160:163], v[48:51]
	s_add_u32 m0, s4, 0xa000
	s_nop 0
	global_load_lds_dwordx4 v58, s[0:1]
	v_mfma_f32_16x16x32_bf16 v[44:47], v[144:147], v[164:167], v[44:47]
	v_mfma_f32_16x16x32_bf16 v[36:39], v[144:147], v[168:171], v[36:39]
	s_add_u32 m0, s4, 0xb000
	s_nop 0
	global_load_lds_dwordx4 v59, s[0:1]
	v_mfma_f32_16x16x32_bf16 v[32:35], v[148:151], v[156:159], v[32:35]
	v_mfma_f32_16x16x32_bf16 v[28:31], v[148:151], v[160:163], v[28:31]
	s_add_u32 m0, s4, 0xc000
	s_nop 0
	global_load_lds_dwordx4 v56, s[2:3]
	v_mfma_f32_16x16x32_bf16 v[24:27], v[148:151], v[164:167], v[24:27]
	v_mfma_f32_16x16x32_bf16 v[20:23], v[148:151], v[168:171], v[20:23]
	s_add_u32 m0, s4, 0xd000
	s_nop 0
	global_load_lds_dwordx4 v57, s[2:3]
	v_mfma_f32_16x16x32_bf16 v[16:19], v[152:155], v[156:159], v[16:19]
	v_mfma_f32_16x16x32_bf16 v[12:15], v[152:155], v[160:163], v[12:15]
	s_add_u32 m0, s4, 0xe000
	s_nop 0
	global_load_lds_dwordx4 v58, s[2:3]
	v_mfma_f32_16x16x32_bf16 v[8:11], v[152:155], v[164:167], v[8:11]
	v_mfma_f32_16x16x32_bf16 v[4:7], v[152:155], v[168:171], v[4:7]
	s_add_u32 m0, s4, 0xf000
	s_nop 0
	global_load_lds_dwordx4 v59, s[2:3]
	s_add_u32 s0, s0, 0x80
	s_addc_u32 s1, s1, 0
	s_add_u32 s2, s2, 0x80
	s_addc_u32 s3, s3, 0
	s_waitcnt vmcnt(0) lgkmcnt(0)
	s_barrier
	ds_read_b128 v[140:143], v66 offset:32768
	ds_read_b128 v[144:147], v66 offset:34816
	ds_read_b128 v[148:151], v66 offset:36864
	ds_read_b128 v[152:155], v66 offset:38912
	ds_read_b128 v[156:159], v64 offset:32768
	ds_read_b128 v[160:163], v64 offset:34816
	ds_read_b128 v[164:167], v64 offset:36864
	ds_read_b128 v[168:171], v64 offset:38912
	v_mfma_f32_16x16x32_bf16 v[60:63], v[172:175], v[188:191], v[60:63]
	v_mfma_f32_16x16x32_bf16 v[68:71], v[172:175], v[192:195], v[68:71]
	v_mfma_f32_16x16x32_bf16 v[52:55], v[172:175], v[196:199], v[52:55]
	v_mfma_f32_16x16x32_bf16 v[40:43], v[172:175], v[200:203], v[40:43]
	v_mfma_f32_16x16x32_bf16 v[72:75], v[176:179], v[188:191], v[72:75]
	v_mfma_f32_16x16x32_bf16 v[48:51], v[176:179], v[192:195], v[48:51]
	v_mfma_f32_16x16x32_bf16 v[44:47], v[176:179], v[196:199], v[44:47]
	v_mfma_f32_16x16x32_bf16 v[36:39], v[176:179], v[200:203], v[36:39]
	v_mfma_f32_16x16x32_bf16 v[32:35], v[180:183], v[188:191], v[32:35]
	v_mfma_f32_16x16x32_bf16 v[28:31], v[180:183], v[192:195], v[28:31]
	v_mfma_f32_16x16x32_bf16 v[24:27], v[180:183], v[196:199], v[24:27]
	v_mfma_f32_16x16x32_bf16 v[20:23], v[180:183], v[200:203], v[20:23]
	v_mfma_f32_16x16x32_bf16 v[16:19], v[184:187], v[188:191], v[16:19]
	v_mfma_f32_16x16x32_bf16 v[12:15], v[184:187], v[192:195], v[12:15]
	v_mfma_f32_16x16x32_bf16 v[8:11], v[184:187], v[196:199], v[8:11]
	v_mfma_f32_16x16x32_bf16 v[4:7], v[184:187], v[200:203], v[4:7]
	s_waitcnt lgkmcnt(0)
	ds_read_b128 v[172:175], v67 offset:32768
	ds_read_b128 v[176:179], v67 offset:34816
	ds_read_b128 v[180:183], v67 offset:36864
	ds_read_b128 v[184:187], v67 offset:38912
	ds_read_b128 v[188:191], v65 offset:32768
	ds_read_b128 v[192:195], v65 offset:34816
	ds_read_b128 v[196:199], v65 offset:36864
	ds_read_b128 v[200:203], v65 offset:38912
	v_mfma_f32_16x16x32_bf16 v[60:63], v[140:143], v[156:159], v[60:63]
	v_mfma_f32_16x16x32_bf16 v[68:71], v[140:143], v[160:163], v[68:71]
	s_add_u32 m0, s4, 0x0
	s_nop 0
	global_load_lds_dwordx4 v56, s[0:1]
	v_mfma_f32_16x16x32_bf16 v[52:55], v[140:143], v[164:167], v[52:55]
	v_mfma_f32_16x16x32_bf16 v[40:43], v[140:143], v[168:171], v[40:43]
	s_add_u32 m0, s4, 0x1000
	s_nop 0
	global_load_lds_dwordx4 v57, s[0:1]
	v_mfma_f32_16x16x32_bf16 v[72:75], v[144:147], v[156:159], v[72:75]
	v_mfma_f32_16x16x32_bf16 v[48:51], v[144:147], v[160:163], v[48:51]
	s_add_u32 m0, s4, 0x2000
	s_nop 0
	global_load_lds_dwordx4 v58, s[0:1]
	v_mfma_f32_16x16x32_bf16 v[44:47], v[144:147], v[164:167], v[44:47]
	v_mfma_f32_16x16x32_bf16 v[36:39], v[144:147], v[168:171], v[36:39]
	s_add_u32 m0, s4, 0x3000
	s_nop 0
	global_load_lds_dwordx4 v59, s[0:1]
	v_mfma_f32_16x16x32_bf16 v[32:35], v[148:151], v[156:159], v[32:35]
	v_mfma_f32_16x16x32_bf16 v[28:31], v[148:151], v[160:163], v[28:31]
	s_add_u32 m0, s4, 0x4000
	s_nop 0
	global_load_lds_dwordx4 v56, s[2:3]
	v_mfma_f32_16x16x32_bf16 v[24:27], v[148:151], v[164:167], v[24:27]
	v_mfma_f32_16x16x32_bf16 v[20:23], v[148:151], v[168:171], v[20:23]
	s_add_u32 m0, s4, 0x5000
	s_nop 0
	global_load_lds_dwordx4 v57, s[2:3]
	v_mfma_f32_16x16x32_bf16 v[16:19], v[152:155], v[156:159], v[16:19]
	v_mfma_f32_16x16x32_bf16 v[12:15], v[152:155], v[160:163], v[12:15]
	s_add_u32 m0, s4, 0x6000
	s_nop 0
	global_load_lds_dwordx4 v58, s[2:3]
	v_mfma_f32_16x16x32_bf16 v[8:11], v[152:155], v[164:167], v[8:11]
	v_mfma_f32_16x16x32_bf16 v[4:7], v[152:155], v[168:171], v[4:7]
	s_add_u32 m0, s4, 0x7000
	s_nop 0
	global_load_lds_dwordx4 v59, s[2:3]
	s_add_u32 s0, s0, 0x80
	s_addc_u32 s1, s1, 0
	s_add_u32 s2, s2, 0x80
	s_addc_u32 s3, s3, 0
	s_waitcnt vmcnt(0) lgkmcnt(0)
	s_barrier
	ds_read_b128 v[140:143], v66 offset:0
	ds_read_b128 v[144:147], v66 offset:2048
	ds_read_b128 v[148:151], v66 offset:4096
	ds_read_b128 v[152:155], v66 offset:6144
	ds_read_b128 v[156:159], v64 offset:0
	ds_read_b128 v[160:163], v64 offset:2048
	ds_read_b128 v[164:167], v64 offset:4096
	ds_read_b128 v[168:171], v64 offset:6144
	v_mfma_f32_16x16x32_bf16 v[60:63], v[172:175], v[188:191], v[60:63]
	v_mfma_f32_16x16x32_bf16 v[68:71], v[172:175], v[192:195], v[68:71]
	v_mfma_f32_16x16x32_bf16 v[52:55], v[172:175], v[196:199], v[52:55]
	v_mfma_f32_16x16x32_bf16 v[40:43], v[172:175], v[200:203], v[40:43]
	v_mfma_f32_16x16x32_bf16 v[72:75], v[176:179], v[188:191], v[72:75]
	v_mfma_f32_16x16x32_bf16 v[48:51], v[176:179], v[192:195], v[48:51]
	v_mfma_f32_16x16x32_bf16 v[44:47], v[176:179], v[196:199], v[44:47]
	v_mfma_f32_16x16x32_bf16 v[36:39], v[176:179], v[200:203], v[36:39]
	v_mfma_f32_16x16x32_bf16 v[32:35], v[180:183], v[188:191], v[32:35]
	v_mfma_f32_16x16x32_bf16 v[28:31], v[180:183], v[192:195], v[28:31]
	v_mfma_f32_16x16x32_bf16 v[24:27], v[180:183], v[196:199], v[24:27]
	v_mfma_f32_16x16x32_bf16 v[20:23], v[180:183], v[200:203], v[20:23]
	v_mfma_f32_16x16x32_bf16 v[16:19], v[184:187], v[188:191], v[16:19]
	v_mfma_f32_16x16x32_bf16 v[12:15], v[184:187], v[192:195], v[12:15]
	v_mfma_f32_16x16x32_bf16 v[8:11], v[184:187], v[196:199], v[8:11]
	v_mfma_f32_16x16x32_bf16 v[4:7], v[184:187], v[200:203], v[4:7]
	s_waitcnt lgkmcnt(0)
	ds_read_b128 v[172:175], v67 offset:0
	ds_read_b128 v[176:179], v67 offset:2048
	ds_read_b128 v[180:183], v67 offset:4096
	ds_read_b128 v[184:187], v67 offset:6144
	ds_read_b128 v[188:191], v65 offset:0
	ds_read_b128 v[192:195], v65 offset:2048
	ds_read_b128 v[196:199], v65 offset:4096
	ds_read_b128 v[200:203], v65 offset:6144
	v_mfma_f32_16x16x32_bf16 v[60:63], v[140:143], v[156:159], v[60:63]
	v_mfma_f32_16x16x32_bf16 v[68:71], v[140:143], v[160:163], v[68:71]
	s_add_u32 m0, s4, 0x8000
	s_nop 0
	global_load_lds_dwordx4 v56, s[0:1]
	v_mfma_f32_16x16x32_bf16 v[52:55], v[140:143], v[164:167], v[52:55]
	v_mfma_f32_16x16x32_bf16 v[40:43], v[140:143], v[168:171], v[40:43]
	s_add_u32 m0, s4, 0x9000
	s_nop 0
	global_load_lds_dwordx4 v57, s[0:1]
	v_mfma_f32_16x16x32_bf16 v[72:75], v[144:147], v[156:159], v[72:75]
	v_mfma_f32_16x16x32_bf16 v[48:51], v[144:147], v[160:163], v[48:51]
	s_add_u32 m0, s4, 0xa000
	s_nop 0
	global_load_lds_dwordx4 v58, s[0:1]
	v_mfma_f32_16x16x32_bf16 v[44:47], v[144:147], v[164:167], v[44:47]
	v_mfma_f32_16x16x32_bf16 v[36:39], v[144:147], v[168:171], v[36:39]
	s_add_u32 m0, s4, 0xb000
	s_nop 0
	global_load_lds_dwordx4 v59, s[0:1]
	v_mfma_f32_16x16x32_bf16 v[32:35], v[148:151], v[156:159], v[32:35]
	v_mfma_f32_16x16x32_bf16 v[28:31], v[148:151], v[160:163], v[28:31]
	s_add_u32 m0, s4, 0xc000
	s_nop 0
	global_load_lds_dwordx4 v56, s[2:3]
	v_mfma_f32_16x16x32_bf16 v[24:27], v[148:151], v[164:167], v[24:27]
	v_mfma_f32_16x16x32_bf16 v[20:23], v[148:151], v[168:171], v[20:23]
	s_add_u32 m0, s4, 0xd000
	s_nop 0
	global_load_lds_dwordx4 v57, s[2:3]
	v_mfma_f32_16x16x32_bf16 v[16:19], v[152:155], v[156:159], v[16:19]
	v_mfma_f32_16x16x32_bf16 v[12:15], v[152:155], v[160:163], v[12:15]
	s_add_u32 m0, s4, 0xe000
	s_nop 0
	global_load_lds_dwordx4 v58, s[2:3]
	v_mfma_f32_16x16x32_bf16 v[8:11], v[152:155], v[164:167], v[8:11]
	v_mfma_f32_16x16x32_bf16 v[4:7], v[152:155], v[168:171], v[4:7]
	s_add_u32 m0, s4, 0xf000
	s_nop 0
	global_load_lds_dwordx4 v59, s[2:3]
	s_add_u32 s0, s0, 0x80
	s_addc_u32 s1, s1, 0
	s_add_u32 s2, s2, 0x80
	s_addc_u32 s3, s3, 0
	s_waitcnt vmcnt(0) lgkmcnt(0)
	s_barrier
	ds_read_b128 v[140:143], v66 offset:32768
	ds_read_b128 v[144:147], v66 offset:34816
	ds_read_b128 v[148:151], v66 offset:36864
	ds_read_b128 v[152:155], v66 offset:38912
	ds_read_b128 v[156:159], v64 offset:32768
	ds_read_b128 v[160:163], v64 offset:34816
	ds_read_b128 v[164:167], v64 offset:36864
	ds_read_b128 v[168:171], v64 offset:38912
	v_mfma_f32_16x16x32_bf16 v[60:63], v[172:175], v[188:191], v[60:63]
	v_mfma_f32_16x16x32_bf16 v[68:71], v[172:175], v[192:195], v[68:71]
	v_mfma_f32_16x16x32_bf16 v[52:55], v[172:175], v[196:199], v[52:55]
	v_mfma_f32_16x16x32_bf16 v[40:43], v[172:175], v[200:203], v[40:43]
	v_mfma_f32_16x16x32_bf16 v[72:75], v[176:179], v[188:191], v[72:75]
	v_mfma_f32_16x16x32_bf16 v[48:51], v[176:179], v[192:195], v[48:51]
	v_mfma_f32_16x16x32_bf16 v[44:47], v[176:179], v[196:199], v[44:47]
	v_mfma_f32_16x16x32_bf16 v[36:39], v[176:179], v[200:203], v[36:39]
	v_mfma_f32_16x16x32_bf16 v[32:35], v[180:183], v[188:191], v[32:35]
	v_mfma_f32_16x16x32_bf16 v[28:31], v[180:183], v[192:195], v[28:31]
	v_mfma_f32_16x16x32_bf16 v[24:27], v[180:183], v[196:199], v[24:27]
	v_mfma_f32_16x16x32_bf16 v[20:23], v[180:183], v[200:203], v[20:23]
	v_mfma_f32_16x16x32_bf16 v[16:19], v[184:187], v[188:191], v[16:19]
	v_mfma_f32_16x16x32_bf16 v[12:15], v[184:187], v[192:195], v[12:15]
	v_mfma_f32_16x16x32_bf16 v[8:11], v[184:187], v[196:199], v[8:11]
	v_mfma_f32_16x16x32_bf16 v[4:7], v[184:187], v[200:203], v[4:7]
	s_waitcnt lgkmcnt(0)
	ds_read_b128 v[172:175], v67 offset:32768
	ds_read_b128 v[176:179], v67 offset:34816
	ds_read_b128 v[180:183], v67 offset:36864
	ds_read_b128 v[184:187], v67 offset:38912
	ds_read_b128 v[188:191], v65 offset:32768
	ds_read_b128 v[192:195], v65 offset:34816
	ds_read_b128 v[196:199], v65 offset:36864
	ds_read_b128 v[200:203], v65 offset:38912
	v_mfma_f32_16x16x32_bf16 v[60:63], v[140:143], v[156:159], v[60:63]
	v_mfma_f32_16x16x32_bf16 v[68:71], v[140:143], v[160:163], v[68:71]
	s_add_u32 m0, s4, 0x0
	s_nop 0
	global_load_lds_dwordx4 v56, s[0:1]
	v_mfma_f32_16x16x32_bf16 v[52:55], v[140:143], v[164:167], v[52:55]
	v_mfma_f32_16x16x32_bf16 v[40:43], v[140:143], v[168:171], v[40:43]
	s_add_u32 m0, s4, 0x1000
	s_nop 0
	global_load_lds_dwordx4 v57, s[0:1]
	v_mfma_f32_16x16x32_bf16 v[72:75], v[144:147], v[156:159], v[72:75]
	v_mfma_f32_16x16x32_bf16 v[48:51], v[144:147], v[160:163], v[48:51]
	s_add_u32 m0, s4, 0x2000
	s_nop 0
	global_load_lds_dwordx4 v58, s[0:1]
	v_mfma_f32_16x16x32_bf16 v[44:47], v[144:147], v[164:167], v[44:47]
	v_mfma_f32_16x16x32_bf16 v[36:39], v[144:147], v[168:171], v[36:39]
	s_add_u32 m0, s4, 0x3000
	s_nop 0
	global_load_lds_dwordx4 v59, s[0:1]
	v_mfma_f32_16x16x32_bf16 v[32:35], v[148:151], v[156:159], v[32:35]
	v_mfma_f32_16x16x32_bf16 v[28:31], v[148:151], v[160:163], v[28:31]
	s_add_u32 m0, s4, 0x4000
	s_nop 0
	global_load_lds_dwordx4 v56, s[2:3]
	v_mfma_f32_16x16x32_bf16 v[24:27], v[148:151], v[164:167], v[24:27]
	v_mfma_f32_16x16x32_bf16 v[20:23], v[148:151], v[168:171], v[20:23]
	s_add_u32 m0, s4, 0x5000
	s_nop 0
	global_load_lds_dwordx4 v57, s[2:3]
	v_mfma_f32_16x16x32_bf16 v[16:19], v[152:155], v[156:159], v[16:19]
	v_mfma_f32_16x16x32_bf16 v[12:15], v[152:155], v[160:163], v[12:15]
	s_add_u32 m0, s4, 0x6000
	s_nop 0
	global_load_lds_dwordx4 v58, s[2:3]
	v_mfma_f32_16x16x32_bf16 v[8:11], v[152:155], v[164:167], v[8:11]
	v_mfma_f32_16x16x32_bf16 v[4:7], v[152:155], v[168:171], v[4:7]
	s_add_u32 m0, s4, 0x7000
	s_nop 0
	global_load_lds_dwordx4 v59, s[2:3]
	s_add_u32 s0, s0, 0x80
	s_addc_u32 s1, s1, 0
	s_add_u32 s2, s2, 0x80
	s_addc_u32 s3, s3, 0
	s_waitcnt vmcnt(0) lgkmcnt(0)
	s_barrier
	ds_read_b128 v[140:143], v66 offset:0
	ds_read_b128 v[144:147], v66 offset:2048
	ds_read_b128 v[148:151], v66 offset:4096
	ds_read_b128 v[152:155], v66 offset:6144
	ds_read_b128 v[156:159], v64 offset:0
	ds_read_b128 v[160:163], v64 offset:2048
	ds_read_b128 v[164:167], v64 offset:4096
	ds_read_b128 v[168:171], v64 offset:6144
	v_mfma_f32_16x16x32_bf16 v[60:63], v[172:175], v[188:191], v[60:63]
	v_mfma_f32_16x16x32_bf16 v[68:71], v[172:175], v[192:195], v[68:71]
	v_mfma_f32_16x16x32_bf16 v[52:55], v[172:175], v[196:199], v[52:55]
	v_mfma_f32_16x16x32_bf16 v[40:43], v[172:175], v[200:203], v[40:43]
	v_mfma_f32_16x16x32_bf16 v[72:75], v[176:179], v[188:191], v[72:75]
	v_mfma_f32_16x16x32_bf16 v[48:51], v[176:179], v[192:195], v[48:51]
	v_mfma_f32_16x16x32_bf16 v[44:47], v[176:179], v[196:199], v[44:47]
	v_mfma_f32_16x16x32_bf16 v[36:39], v[176:179], v[200:203], v[36:39]
	v_mfma_f32_16x16x32_bf16 v[32:35], v[180:183], v[188:191], v[32:35]
	v_mfma_f32_16x16x32_bf16 v[28:31], v[180:183], v[192:195], v[28:31]
	v_mfma_f32_16x16x32_bf16 v[24:27], v[180:183], v[196:199], v[24:27]
	v_mfma_f32_16x16x32_bf16 v[20:23], v[180:183], v[200:203], v[20:23]
	v_mfma_f32_16x16x32_bf16 v[16:19], v[184:187], v[188:191], v[16:19]
	v_mfma_f32_16x16x32_bf16 v[12:15], v[184:187], v[192:195], v[12:15]
	v_mfma_f32_16x16x32_bf16 v[8:11], v[184:187], v[196:199], v[8:11]
	v_mfma_f32_16x16x32_bf16 v[4:7], v[184:187], v[200:203], v[4:7]
	s_waitcnt lgkmcnt(0)
	ds_read_b128 v[172:175], v67 offset:0
	ds_read_b128 v[176:179], v67 offset:2048
	ds_read_b128 v[180:183], v67 offset:4096
	ds_read_b128 v[184:187], v67 offset:6144
	ds_read_b128 v[188:191], v65 offset:0
	ds_read_b128 v[192:195], v65 offset:2048
	ds_read_b128 v[196:199], v65 offset:4096
	ds_read_b128 v[200:203], v65 offset:6144
	v_mfma_f32_16x16x32_bf16 v[60:63], v[140:143], v[156:159], v[60:63]
	v_mfma_f32_16x16x32_bf16 v[68:71], v[140:143], v[160:163], v[68:71]
	s_add_u32 m0, s4, 0x8000
	s_nop 0
	global_load_lds_dwordx4 v56, s[0:1]
	v_mfma_f32_16x16x32_bf16 v[52:55], v[140:143], v[164:167], v[52:55]
	v_mfma_f32_16x16x32_bf16 v[40:43], v[140:143], v[168:171], v[40:43]
	s_add_u32 m0, s4, 0x9000
	s_nop 0
	global_load_lds_dwordx4 v57, s[0:1]
	v_mfma_f32_16x16x32_bf16 v[72:75], v[144:147], v[156:159], v[72:75]
	v_mfma_f32_16x16x32_bf16 v[48:51], v[144:147], v[160:163], v[48:51]
	s_add_u32 m0, s4, 0xa000
	s_nop 0
	global_load_lds_dwordx4 v58, s[0:1]
	v_mfma_f32_16x16x32_bf16 v[44:47], v[144:147], v[164:167], v[44:47]
	v_mfma_f32_16x16x32_bf16 v[36:39], v[144:147], v[168:171], v[36:39]
	s_add_u32 m0, s4, 0xb000
	s_nop 0
	global_load_lds_dwordx4 v59, s[0:1]
	v_mfma_f32_16x16x32_bf16 v[32:35], v[148:151], v[156:159], v[32:35]
	v_mfma_f32_16x16x32_bf16 v[28:31], v[148:151], v[160:163], v[28:31]
	s_add_u32 m0, s4, 0xc000
	s_nop 0
	global_load_lds_dwordx4 v56, s[2:3]
	v_mfma_f32_16x16x32_bf16 v[24:27], v[148:151], v[164:167], v[24:27]
	v_mfma_f32_16x16x32_bf16 v[20:23], v[148:151], v[168:171], v[20:23]
	s_add_u32 m0, s4, 0xd000
	s_nop 0
	global_load_lds_dwordx4 v57, s[2:3]
	v_mfma_f32_16x16x32_bf16 v[16:19], v[152:155], v[156:159], v[16:19]
	v_mfma_f32_16x16x32_bf16 v[12:15], v[152:155], v[160:163], v[12:15]
	s_add_u32 m0, s4, 0xe000
	s_nop 0
	global_load_lds_dwordx4 v58, s[2:3]
	v_mfma_f32_16x16x32_bf16 v[8:11], v[152:155], v[164:167], v[8:11]
	v_mfma_f32_16x16x32_bf16 v[4:7], v[152:155], v[168:171], v[4:7]
	s_add_u32 m0, s4, 0xf000
	s_nop 0
	global_load_lds_dwordx4 v59, s[2:3]
	s_add_u32 s0, s0, 0x80
	s_addc_u32 s1, s1, 0
	s_add_u32 s2, s2, 0x80
	s_addc_u32 s3, s3, 0
	s_waitcnt vmcnt(0) lgkmcnt(0)
	s_barrier
	ds_read_b128 v[140:143], v66 offset:32768
	ds_read_b128 v[144:147], v66 offset:34816
	ds_read_b128 v[148:151], v66 offset:36864
	ds_read_b128 v[152:155], v66 offset:38912
	ds_read_b128 v[156:159], v64 offset:32768
	ds_read_b128 v[160:163], v64 offset:34816
	ds_read_b128 v[164:167], v64 offset:36864
	ds_read_b128 v[168:171], v64 offset:38912
	v_mfma_f32_16x16x32_bf16 v[60:63], v[172:175], v[188:191], v[60:63]
	v_mfma_f32_16x16x32_bf16 v[68:71], v[172:175], v[192:195], v[68:71]
	v_mfma_f32_16x16x32_bf16 v[52:55], v[172:175], v[196:199], v[52:55]
	v_mfma_f32_16x16x32_bf16 v[40:43], v[172:175], v[200:203], v[40:43]
	v_mfma_f32_16x16x32_bf16 v[72:75], v[176:179], v[188:191], v[72:75]
	v_mfma_f32_16x16x32_bf16 v[48:51], v[176:179], v[192:195], v[48:51]
	v_mfma_f32_16x16x32_bf16 v[44:47], v[176:179], v[196:199], v[44:47]
	v_mfma_f32_16x16x32_bf16 v[36:39], v[176:179], v[200:203], v[36:39]
	v_mfma_f32_16x16x32_bf16 v[32:35], v[180:183], v[188:191], v[32:35]
	v_mfma_f32_16x16x32_bf16 v[28:31], v[180:183], v[192:195], v[28:31]
	v_mfma_f32_16x16x32_bf16 v[24:27], v[180:183], v[196:199], v[24:27]
	v_mfma_f32_16x16x32_bf16 v[20:23], v[180:183], v[200:203], v[20:23]
	v_mfma_f32_16x16x32_bf16 v[16:19], v[184:187], v[188:191], v[16:19]
	v_mfma_f32_16x16x32_bf16 v[12:15], v[184:187], v[192:195], v[12:15]
	v_mfma_f32_16x16x32_bf16 v[8:11], v[184:187], v[196:199], v[8:11]
	v_mfma_f32_16x16x32_bf16 v[4:7], v[184:187], v[200:203], v[4:7]
	s_waitcnt lgkmcnt(0)
	ds_read_b128 v[172:175], v67 offset:32768
	ds_read_b128 v[176:179], v67 offset:34816
	ds_read_b128 v[180:183], v67 offset:36864
	ds_read_b128 v[184:187], v67 offset:38912
	ds_read_b128 v[188:191], v65 offset:32768
	ds_read_b128 v[192:195], v65 offset:34816
	ds_read_b128 v[196:199], v65 offset:36864
	ds_read_b128 v[200:203], v65 offset:38912
	v_mfma_f32_16x16x32_bf16 v[60:63], v[140:143], v[156:159], v[60:63]
	v_mfma_f32_16x16x32_bf16 v[68:71], v[140:143], v[160:163], v[68:71]
	s_add_u32 m0, s4, 0x0
	s_nop 0
	global_load_lds_dwordx4 v56, s[0:1]
	v_mfma_f32_16x16x32_bf16 v[52:55], v[140:143], v[164:167], v[52:55]
	v_mfma_f32_16x16x32_bf16 v[40:43], v[140:143], v[168:171], v[40:43]
	s_add_u32 m0, s4, 0x1000
	s_nop 0
	global_load_lds_dwordx4 v57, s[0:1]
	v_mfma_f32_16x16x32_bf16 v[72:75], v[144:147], v[156:159], v[72:75]
	v_mfma_f32_16x16x32_bf16 v[48:51], v[144:147], v[160:163], v[48:51]
	s_add_u32 m0, s4, 0x2000
	s_nop 0
	global_load_lds_dwordx4 v58, s[0:1]
	v_mfma_f32_16x16x32_bf16 v[44:47], v[144:147], v[164:167], v[44:47]
	v_mfma_f32_16x16x32_bf16 v[36:39], v[144:147], v[168:171], v[36:39]
	s_add_u32 m0, s4, 0x3000
	s_nop 0
	global_load_lds_dwordx4 v59, s[0:1]
	v_mfma_f32_16x16x32_bf16 v[32:35], v[148:151], v[156:159], v[32:35]
	v_mfma_f32_16x16x32_bf16 v[28:31], v[148:151], v[160:163], v[28:31]
	s_add_u32 m0, s4, 0x4000
	s_nop 0
	global_load_lds_dwordx4 v56, s[2:3]
	v_mfma_f32_16x16x32_bf16 v[24:27], v[148:151], v[164:167], v[24:27]
	v_mfma_f32_16x16x32_bf16 v[20:23], v[148:151], v[168:171], v[20:23]
	s_add_u32 m0, s4, 0x5000
	s_nop 0
	global_load_lds_dwordx4 v57, s[2:3]
	v_mfma_f32_16x16x32_bf16 v[16:19], v[152:155], v[156:159], v[16:19]
	v_mfma_f32_16x16x32_bf16 v[12:15], v[152:155], v[160:163], v[12:15]
	s_add_u32 m0, s4, 0x6000
	s_nop 0
	global_load_lds_dwordx4 v58, s[2:3]
	v_mfma_f32_16x16x32_bf16 v[8:11], v[152:155], v[164:167], v[8:11]
	v_mfma_f32_16x16x32_bf16 v[4:7], v[152:155], v[168:171], v[4:7]
	s_add_u32 m0, s4, 0x7000
	s_nop 0
	global_load_lds_dwordx4 v59, s[2:3]
	s_add_u32 s0, s0, 0x80
	s_addc_u32 s1, s1, 0
	s_add_u32 s2, s2, 0x80
	s_addc_u32 s3, s3, 0
	s_waitcnt vmcnt(0) lgkmcnt(0)
	s_barrier
	ds_read_b128 v[140:143], v66 offset:0
	ds_read_b128 v[144:147], v66 offset:2048
	ds_read_b128 v[148:151], v66 offset:4096
	ds_read_b128 v[152:155], v66 offset:6144
	ds_read_b128 v[156:159], v64 offset:0
	ds_read_b128 v[160:163], v64 offset:2048
	ds_read_b128 v[164:167], v64 offset:4096
	ds_read_b128 v[168:171], v64 offset:6144
	v_mfma_f32_16x16x32_bf16 v[60:63], v[172:175], v[188:191], v[60:63]
	v_mfma_f32_16x16x32_bf16 v[68:71], v[172:175], v[192:195], v[68:71]
	v_mfma_f32_16x16x32_bf16 v[52:55], v[172:175], v[196:199], v[52:55]
	v_mfma_f32_16x16x32_bf16 v[40:43], v[172:175], v[200:203], v[40:43]
	v_mfma_f32_16x16x32_bf16 v[72:75], v[176:179], v[188:191], v[72:75]
	v_mfma_f32_16x16x32_bf16 v[48:51], v[176:179], v[192:195], v[48:51]
	v_mfma_f32_16x16x32_bf16 v[44:47], v[176:179], v[196:199], v[44:47]
	v_mfma_f32_16x16x32_bf16 v[36:39], v[176:179], v[200:203], v[36:39]
	v_mfma_f32_16x16x32_bf16 v[32:35], v[180:183], v[188:191], v[32:35]
	v_mfma_f32_16x16x32_bf16 v[28:31], v[180:183], v[192:195], v[28:31]
	v_mfma_f32_16x16x32_bf16 v[24:27], v[180:183], v[196:199], v[24:27]
	v_mfma_f32_16x16x32_bf16 v[20:23], v[180:183], v[200:203], v[20:23]
	v_mfma_f32_16x16x32_bf16 v[16:19], v[184:187], v[188:191], v[16:19]
	v_mfma_f32_16x16x32_bf16 v[12:15], v[184:187], v[192:195], v[12:15]
	v_mfma_f32_16x16x32_bf16 v[8:11], v[184:187], v[196:199], v[8:11]
	v_mfma_f32_16x16x32_bf16 v[4:7], v[184:187], v[200:203], v[4:7]
	s_waitcnt lgkmcnt(0)
	ds_read_b128 v[172:175], v67 offset:0
	ds_read_b128 v[176:179], v67 offset:2048
	ds_read_b128 v[180:183], v67 offset:4096
	ds_read_b128 v[184:187], v67 offset:6144
	ds_read_b128 v[188:191], v65 offset:0
	ds_read_b128 v[192:195], v65 offset:2048
	ds_read_b128 v[196:199], v65 offset:4096
	ds_read_b128 v[200:203], v65 offset:6144
	v_mfma_f32_16x16x32_bf16 v[60:63], v[140:143], v[156:159], v[60:63]
	v_mfma_f32_16x16x32_bf16 v[68:71], v[140:143], v[160:163], v[68:71]
	s_add_u32 m0, s4, 0x8000
	s_nop 0
	global_load_lds_dwordx4 v56, s[0:1]
	v_mfma_f32_16x16x32_bf16 v[52:55], v[140:143], v[164:167], v[52:55]
	v_mfma_f32_16x16x32_bf16 v[40:43], v[140:143], v[168:171], v[40:43]
	s_add_u32 m0, s4, 0x9000
	s_nop 0
	global_load_lds_dwordx4 v57, s[0:1]
	v_mfma_f32_16x16x32_bf16 v[72:75], v[144:147], v[156:159], v[72:75]
	v_mfma_f32_16x16x32_bf16 v[48:51], v[144:147], v[160:163], v[48:51]
	s_add_u32 m0, s4, 0xa000
	s_nop 0
	global_load_lds_dwordx4 v58, s[0:1]
	v_mfma_f32_16x16x32_bf16 v[44:47], v[144:147], v[164:167], v[44:47]
	v_mfma_f32_16x16x32_bf16 v[36:39], v[144:147], v[168:171], v[36:39]
	s_add_u32 m0, s4, 0xb000
	s_nop 0
	global_load_lds_dwordx4 v59, s[0:1]
	v_mfma_f32_16x16x32_bf16 v[32:35], v[148:151], v[156:159], v[32:35]
	v_mfma_f32_16x16x32_bf16 v[28:31], v[148:151], v[160:163], v[28:31]
	s_add_u32 m0, s4, 0xc000
	s_nop 0
	global_load_lds_dwordx4 v56, s[2:3]
	v_mfma_f32_16x16x32_bf16 v[24:27], v[148:151], v[164:167], v[24:27]
	v_mfma_f32_16x16x32_bf16 v[20:23], v[148:151], v[168:171], v[20:23]
	s_add_u32 m0, s4, 0xd000
	s_nop 0
	global_load_lds_dwordx4 v57, s[2:3]
	v_mfma_f32_16x16x32_bf16 v[16:19], v[152:155], v[156:159], v[16:19]
	v_mfma_f32_16x16x32_bf16 v[12:15], v[152:155], v[160:163], v[12:15]
	s_add_u32 m0, s4, 0xe000
	s_nop 0
	global_load_lds_dwordx4 v58, s[2:3]
	v_mfma_f32_16x16x32_bf16 v[8:11], v[152:155], v[164:167], v[8:11]
	v_mfma_f32_16x16x32_bf16 v[4:7], v[152:155], v[168:171], v[4:7]
	s_add_u32 m0, s4, 0xf000
	s_nop 0
	global_load_lds_dwordx4 v59, s[2:3]
	s_add_u32 s0, s0, 0x80
	s_addc_u32 s1, s1, 0
	s_add_u32 s2, s2, 0x80
	s_addc_u32 s3, s3, 0
	s_waitcnt vmcnt(0) lgkmcnt(0)
	s_barrier
	ds_read_b128 v[140:143], v66 offset:32768
	ds_read_b128 v[144:147], v66 offset:34816
	ds_read_b128 v[148:151], v66 offset:36864
	ds_read_b128 v[152:155], v66 offset:38912
	ds_read_b128 v[156:159], v64 offset:32768
	ds_read_b128 v[160:163], v64 offset:34816
	ds_read_b128 v[164:167], v64 offset:36864
	ds_read_b128 v[168:171], v64 offset:38912
	v_mfma_f32_16x16x32_bf16 v[60:63], v[172:175], v[188:191], v[60:63]
	v_mfma_f32_16x16x32_bf16 v[68:71], v[172:175], v[192:195], v[68:71]
	v_mfma_f32_16x16x32_bf16 v[52:55], v[172:175], v[196:199], v[52:55]
	v_mfma_f32_16x16x32_bf16 v[40:43], v[172:175], v[200:203], v[40:43]
	v_mfma_f32_16x16x32_bf16 v[72:75], v[176:179], v[188:191], v[72:75]
	v_mfma_f32_16x16x32_bf16 v[48:51], v[176:179], v[192:195], v[48:51]
	v_mfma_f32_16x16x32_bf16 v[44:47], v[176:179], v[196:199], v[44:47]
	v_mfma_f32_16x16x32_bf16 v[36:39], v[176:179], v[200:203], v[36:39]
	v_mfma_f32_16x16x32_bf16 v[32:35], v[180:183], v[188:191], v[32:35]
	v_mfma_f32_16x16x32_bf16 v[28:31], v[180:183], v[192:195], v[28:31]
	v_mfma_f32_16x16x32_bf16 v[24:27], v[180:183], v[196:199], v[24:27]
	v_mfma_f32_16x16x32_bf16 v[20:23], v[180:183], v[200:203], v[20:23]
	v_mfma_f32_16x16x32_bf16 v[16:19], v[184:187], v[188:191], v[16:19]
	v_mfma_f32_16x16x32_bf16 v[12:15], v[184:187], v[192:195], v[12:15]
	v_mfma_f32_16x16x32_bf16 v[8:11], v[184:187], v[196:199], v[8:11]
	v_mfma_f32_16x16x32_bf16 v[4:7], v[184:187], v[200:203], v[4:7]
	s_waitcnt lgkmcnt(0)
	ds_read_b128 v[172:175], v67 offset:32768
	ds_read_b128 v[176:179], v67 offset:34816
	ds_read_b128 v[180:183], v67 offset:36864
	ds_read_b128 v[184:187], v67 offset:38912
	ds_read_b128 v[188:191], v65 offset:32768
	ds_read_b128 v[192:195], v65 offset:34816
	ds_read_b128 v[196:199], v65 offset:36864
	ds_read_b128 v[200:203], v65 offset:38912
	v_mfma_f32_16x16x32_bf16 v[60:63], v[140:143], v[156:159], v[60:63]
	v_mfma_f32_16x16x32_bf16 v[68:71], v[140:143], v[160:163], v[68:71]
	v_mfma_f32_16x16x32_bf16 v[52:55], v[140:143], v[164:167], v[52:55]
	v_mfma_f32_16x16x32_bf16 v[40:43], v[140:143], v[168:171], v[40:43]
	v_mfma_f32_16x16x32_bf16 v[72:75], v[144:147], v[156:159], v[72:75]
	v_mfma_f32_16x16x32_bf16 v[48:51], v[144:147], v[160:163], v[48:51]
	v_mfma_f32_16x16x32_bf16 v[44:47], v[144:147], v[164:167], v[44:47]
	v_mfma_f32_16x16x32_bf16 v[36:39], v[144:147], v[168:171], v[36:39]
	v_mfma_f32_16x16x32_bf16 v[32:35], v[148:151], v[156:159], v[32:35]
	v_mfma_f32_16x16x32_bf16 v[28:31], v[148:151], v[160:163], v[28:31]
	v_mfma_f32_16x16x32_bf16 v[24:27], v[148:151], v[164:167], v[24:27]
	v_mfma_f32_16x16x32_bf16 v[20:23], v[148:151], v[168:171], v[20:23]
	v_mfma_f32_16x16x32_bf16 v[16:19], v[152:155], v[156:159], v[16:19]
	v_mfma_f32_16x16x32_bf16 v[12:15], v[152:155], v[160:163], v[12:15]
	v_mfma_f32_16x16x32_bf16 v[8:11], v[152:155], v[164:167], v[8:11]
	v_mfma_f32_16x16x32_bf16 v[4:7], v[152:155], v[168:171], v[4:7]
	s_waitcnt vmcnt(0) lgkmcnt(0)
	s_barrier
	v_mfma_f32_16x16x32_bf16 v[60:63], v[172:175], v[188:191], v[60:63]
	v_mfma_f32_16x16x32_bf16 v[68:71], v[172:175], v[192:195], v[68:71]
	v_mfma_f32_16x16x32_bf16 v[52:55], v[172:175], v[196:199], v[52:55]
	v_mfma_f32_16x16x32_bf16 v[40:43], v[172:175], v[200:203], v[40:43]
	v_mfma_f32_16x16x32_bf16 v[72:75], v[176:179], v[188:191], v[72:75]
	v_mfma_f32_16x16x32_bf16 v[48:51], v[176:179], v[192:195], v[48:51]
	v_mfma_f32_16x16x32_bf16 v[44:47], v[176:179], v[196:199], v[44:47]
	v_mfma_f32_16x16x32_bf16 v[36:39], v[176:179], v[200:203], v[36:39]
	v_mfma_f32_16x16x32_bf16 v[32:35], v[180:183], v[188:191], v[32:35]
	v_mfma_f32_16x16x32_bf16 v[28:31], v[180:183], v[192:195], v[28:31]
	v_mfma_f32_16x16x32_bf16 v[24:27], v[180:183], v[196:199], v[24:27]
	v_mfma_f32_16x16x32_bf16 v[20:23], v[180:183], v[200:203], v[20:23]
	v_mfma_f32_16x16x32_bf16 v[16:19], v[184:187], v[188:191], v[16:19]
	v_mfma_f32_16x16x32_bf16 v[12:15], v[184:187], v[192:195], v[12:15]
	v_mfma_f32_16x16x32_bf16 v[8:11], v[184:187], v[196:199], v[8:11]
	v_mfma_f32_16x16x32_bf16 v[4:7], v[184:187], v[200:203], v[4:7]
	s_branch .Lg1_join

.Lg1_join:
	s_lshl_b32 s8, s22, 7
	v_cmp_gt_i32_e32 vcc, s19, v94
	s_nop 7
	s_nop 1
	s_setprio 1
	s_and_saveexec_b64 s[0:1], vcc
	s_cbranch_execz .LBB0_423
	s_xor_b64 s[4:5], s[58:59], -1
	s_and_b32 s9, s64, 0x1fffffe
	s_cmp_lt_i32 s9, 12
	s_cbranch_scc1 .LBB0_349
	s_cmp_eq_u32 s9, 12
	s_cselect_b64 s[2:3], -1, 0
	s_cbranch_execz .LBB0_350
	s_branch .LBB0_351
